# combination: P8 deferred epilogue blocks + P8 tile-index arithmetic in MFMA shadow + attention KX loads overlapped with first K/V DMA wait
# baseline (speedup 1.0000x reference)
; __device__ __forceinline__ int xcd_remap(int L, int nwg) { const int q = nwg / NXCD, r = nwg % NXCD, xcd = L % NXCD, off = L / NXCD; return (xcd < r ? xcd * (q + 1) : r * (q + 1) + (xcd - r) * q) + off; }
; __device__ __forceinline__ u32x4 pack8(f32x4 v0, f32x4 v1) { u32x4 w; w.x = cvt_pk_bf16(v0[0], v0[1]); w.y = cvt_pk_bf16(v0[2], v0[3]); w.z = cvt_pk_bf16(v1[0], v1[1]); w.w = cvt_pk_bf16(v1[2], v1[3]); return w; }
;     __device__ bool next(int i, Unit& u) const {
;         const long L = (long)i * G + c; if (L >= nwg) return false;
;         const int wgid = xcd_remap((int)L, nwg);
;         const int nig = WGM * nN, gid = wgid / nig, fm = gid * WGM, gsz = (nM - fm) < WGM ? (nM - fm) : WGM;
;         int pm = fm + ((wgid % nig) % gsz); const int pn = (wgid % nig) / gsz;
;         if (perm) { const int x = pm >> 4, j = pm & 15; pm = (j < 8) ? 8 * x + j : 64 + 8 * x + (j - 8); } u.aoff = (size_t)pm * atile; u.boff = (size_t)pn * btile + (size_t)(pm >> 3) * bbatch; u.r0 = pm * BM; u.c0 = pn * BM; u.sel = 0; return true;
;     __device__ __forceinline__ void operator()(Acc& acc, const Unit& u, int wr, int wc, int fr, int fq, PG8_LAS unsigned char* xl) const {
;     ...
;             for (int m = 0; m < 4; ++m) { const int rl = ai * HALF + wr * 64 + m * 16 + fr; const int row = u.r0 + rl; const float s = S[rl], cs = -LOG2E * s, s2 = s * s;
;                 f32x4 o[2];
; #pragma unroll
;                 for (int n = 0; n < 2; ++n) { const f32x4 g = acc[ai][0][m][n], gu = acc[ai][0][m][n] * acc[ai][1][m][n]; f32x4 r;
; #pragma unroll
;                     for (int e = 0; e < 4; ++e) r[e] = gu[e] * (s2 * __builtin_amdgcn_rcpf(1.f + __builtin_amdgcn_exp2f(cs * g[e])));
;                     o[n] = r; }
;                 *(u32x4*)(H + (size_t)row * ldc + (u.c0 >> 1) + wc * 32 + 8 * fq) = pack8(o[0], o[1]); }
.LBB0_822:
.LBB0_824:
	s_add_u32 s73, s2, 0x100
	s_addc_u32 s74, s3, 0
	s_add_u32 s2, s30, 0x40080
	s_nop 0
	s_addc_u32 s3, s31, 0
	s_mov_b32 s75, -2
	ds_read_b128 v[170:173], v164
	ds_read_b128 v[174:177], v164 offset:1024
	ds_read_b128 v[180:183], v164 offset:2048
	ds_read_b128 v[184:187], v164 offset:3072
	ds_read_b128 v[188:191], v165
	ds_read_b128 v[192:195], v165 offset:1024
	ds_read_b128 v[196:199], v165 offset:2048
	ds_read_b128 v[200:203], v165 offset:3072
	s_add_u32 s30, s2, 0xfffc0080
	s_addc_u32 s31, s3, -1
	s_cmp_eq_u32 s75, 12
	s_cselect_b32 s35, s46, s31
	s_cselect_b32 s34, s47, s30
	s_cselect_b32 s31, s70, s74
	s_cselect_b32 s30, s72, s73
	v_lshl_add_u64 v[238:239], s[2:3], 0, v[140:141]
	s_add_i32 m0, s55, 0xc000
	ds_read_b128 v[204:207], v166
	ds_read_b128 v[208:211], v166 offset:1024
	ds_read_b128 v[212:215], v166 offset:2048
	ds_read_b128 v[216:219], v166 offset:3072
	ds_read_b128 v[222:225], v166 offset:4096
	ds_read_b128 v[226:229], v166 offset:5120
	ds_read_b128 v[230:233], v166 offset:6144
	ds_read_b128 v[234:237], v166 offset:7168
	global_load_lds_dwordx4 v[238:239], off
	v_lshl_add_u64 v[238:239], s[2:3], 0, v[138:139]
	s_add_i32 m0, s55, 0xe000
	s_nop 0
	global_load_lds_dwordx4 v[238:239], off
	s_waitcnt vmcnt(8)
	s_waitcnt lgkmcnt(0)
	s_barrier
	s_setprio 1
	s_waitcnt lgkmcnt(0)
	v_mfma_f32_16x16x32_bf16 v[124:127], v[170:173], v[204:207], 0
	s_add_i32 s65, s65, 1
	s_mul_i32 s6, s65, s71
	s_mul_hi_u32 s7, s65, s40
	v_mul_f32_e32 v24, v28, v24
	v_mul_f32_e32 v25, v29, v25
	v_mul_f32_e32 v26, v30, v26
	v_mul_f32_e32 v27, v31, v27
	v_mul_f32_e32 v16, v20, v16
	v_mfma_f32_16x16x32_bf16 v[116:119], v[180:183], v[204:207], 0
	s_add_i32 s7, s7, s6
	s_mul_i32 s6, s65, s40
	s_add_u32 s26, s6, s36
	v_mul_f32_e32 v17, v21, v17
	v_mul_f32_e32 v18, v22, v18
	v_mul_f32_e32 v19, v23, v19
	v_mul_f32_e32 v248, 0xbfb8aa3b, v179
	v_mfma_f32_16x16x32_bf16 v[108:111], v[170:173], v[212:215], 0
	s_addc_u32 s27, s7, s52
	v_cmp_lt_i64_e64 s[6:7], s[26:27], v[142:143]
	s_ashr_i32 s20, s26, 31
	v_mul_f32_e32 v250, v179, v179
	v_mul_f32_e32 v28, v28, v248
	v_mul_f32_e32 v29, v29, v248
	v_mul_f32_e32 v30, v30, v248
	v_mfma_f32_16x16x32_bf16 v[100:103], v[180:183], v[212:215], 0
	s_lshr_b32 s20, s20, 29
	s_add_i32 s20, s26, s20
	s_ashr_i32 s21, s20, 3
	v_mul_f32_e32 v31, v31, v248
	v_mul_f32_e32 v20, v20, v248
	v_mul_f32_e32 v21, v21, v248
	v_mul_f32_e32 v22, v22, v248
	v_mfma_f32_16x16x32_bf16 v[92:95], v[170:173], v[222:225], 0
	s_and_b32 s20, s20, -8
	s_sub_i32 s20, s26, s20
	s_cmp_lt_i32 s20, 0
	v_mul_f32_e32 v23, v23, v248
	v_exp_f32_e32 v28, v28
	v_exp_f32_e32 v29, v29
	v_exp_f32_e32 v30, v30
	v_mfma_f32_16x16x32_bf16 v[84:87], v[180:183], v[222:225], 0
	s_cselect_b32 s22, s53, 0x160
	s_mul_i32 s20, s20, s22
	s_add_i32 s20, s20, s21
	v_exp_f32_e32 v31, v31
	v_exp_f32_e32 v20, v20
	v_exp_f32_e32 v21, v21
	v_exp_f32_e32 v22, v22
	v_mfma_f32_16x16x32_bf16 v[76:79], v[170:173], v[230:233], 0
	s_mul_hi_i32 s21, s20, 0x2e8ba2e9
	s_lshr_b32 s22, s21, 31
	s_ashr_i32 s21, s21, 5
	v_exp_f32_e32 v23, v23
	v_add_f32_e32 v28, 1.0, v28
	v_add_f32_e32 v29, 1.0, v29
	v_add_f32_e32 v30, 1.0, v30
	v_mfma_f32_16x16x32_bf16 v[68:71], v[180:183], v[230:233], 0
	s_add_i32 s21, s21, s22
	s_lshl_b32 s22, s21, 3
	s_sub_i32 s23, 0x80, s22
	v_add_f32_e32 v31, 1.0, v31
	v_add_f32_e32 v20, 1.0, v20
	v_add_f32_e32 v21, 1.0, v21
	v_add_f32_e32 v22, 1.0, v22
	v_mfma_f32_16x16x32_bf16 v[124:127], v[174:177], v[208:211], v[124:127]
	s_min_i32 s23, s23, 8
	s_abs_i32 s26, s23
	v_cvt_f32_u32_e32 v254, s26
	v_add_f32_e32 v23, 1.0, v23
	v_rcp_f32_e32 v28, v28
	v_rcp_f32_e32 v29, v29
	v_rcp_f32_e32 v30, v30
	v_mfma_f32_16x16x32_bf16 v[116:119], v[184:187], v[208:211], v[116:119]
	s_sub_i32 s28, 0, s26
	s_mulk_i32 s21, 0xb0
	s_sub_i32 s20, s20, s21
	v_rcp_f32_e32 v31, v31
	v_rcp_f32_e32 v20, v20
	v_rcp_f32_e32 v21, v21
	v_rcp_f32_e32 v22, v22
	v_mfma_f32_16x16x32_bf16 v[108:111], v[174:177], v[216:219], v[108:111]
	v_rcp_iflag_f32_e32 v254, v254
	s_abs_i32 s21, s20
	s_xor_b32 s27, s20, s23
	v_rcp_f32_e32 v23, v23
	v_mul_f32_e32 v28, v250, v28
	v_mul_f32_e32 v29, v250, v29
	v_mul_f32_e32 v30, v250, v30
	v_mfma_f32_16x16x32_bf16 v[100:103], v[184:187], v[216:219], v[100:103]
	s_ashr_i32 s27, s27, 31
	v_mul_f32_e32 v254, 0x4f7ffffe, v254
	v_cvt_u32_f32_e32 v254, v254
	v_mul_f32_e32 v31, v250, v31
	v_mul_f32_e32 v20, v250, v20
	v_mul_f32_e32 v21, v250, v21
	v_mul_f32_e32 v22, v250, v22
	v_mfma_f32_16x16x32_bf16 v[92:95], v[174:177], v[226:229], v[92:95]
	s_nop 0
	v_readfirstlane_b32 s29, v254
	s_mul_i32 s28, s28, s29
	v_mul_f32_e32 v23, v250, v23
	v_mul_f32_e32 v24, v24, v28
	v_mul_f32_e32 v25, v25, v29
	v_mul_f32_e32 v26, v26, v30
	v_mfma_f32_16x16x32_bf16 v[84:87], v[184:187], v[226:229], v[84:87]
	s_mul_hi_u32 s28, s29, s28
	s_add_i32 s29, s29, s28
	s_mul_hi_u32 s28, s21, s29
	v_mul_f32_e32 v27, v27, v31
	v_mul_f32_e32 v16, v16, v20
	v_mul_f32_e32 v17, v17, v21
	v_mul_f32_e32 v18, v18, v22
	v_mfma_f32_16x16x32_bf16 v[76:79], v[174:177], v[234:237], v[76:79]
	s_mul_i32 s29, s28, s26
	s_sub_i32 s21, s21, s29
	s_add_i32 s100, s28, 1
	v_mul_f32_e32 v19, v19, v23
	v_cvt_pk_bf16_f32 v28, v24, v25
	v_cvt_pk_bf16_f32 v29, v26, v27
	v_cvt_pk_bf16_f32 v30, v16, v17
	v_mfma_f32_16x16x32_bf16 v[68:71], v[184:187], v[234:237], v[68:71]
	s_sub_i32 s29, s21, s26
	s_cmp_ge_u32 s21, s26
	s_cselect_b32 s28, s100, s28
	v_cvt_pk_bf16_f32 v31, v18, v19
	global_store_dwordx4 v[252:253], v[28:31], off
	v_add_co_u32_e32 v252, vcc, 0x16000, v252
	s_nop 1
	s_setprio 0
	s_setprio 1
	v_mfma_f32_16x16x32_bf16 v[120:123], v[188:191], v[204:207], 0
	s_cselect_b32 s21, s29, s21
	s_add_i32 s29, s28, 1
; __device__ __forceinline__ int xcd_remap(int L, int nwg) { const int q = nwg / NXCD, r = nwg % NXCD, xcd = L % NXCD, off = L / NXCD; return (xcd < r ? xcd * (q + 1) : r * (q + 1) + (xcd - r) * q) + off; }
; __device__ __forceinline__ u32x4 pack8(f32x4 v0, f32x4 v1) { u32x4 w; w.x = cvt_pk_bf16(v0[0], v0[1]); w.y = cvt_pk_bf16(v0[2], v0[3]); w.z = cvt_pk_bf16(v1[0], v1[1]); w.w = cvt_pk_bf16(v1[2], v1[3]); return w; }
;     __device__ bool next(int i, Unit& u) const {
;     ...
;         const int wgid = xcd_remap((int)L, nwg);
;         const int nig = WGM * nN, gid = wgid / nig, fm = gid * WGM, gsz = (nM - fm) < WGM ? (nM - fm) : WGM;
;         int pm = fm + ((wgid % nig) % gsz); const int pn = (wgid % nig) / gsz;
;         if (perm) { const int x = pm >> 4, j = pm & 15; pm = (j < 8) ? 8 * x + j : 64 + 8 * x + (j - 8); } u.aoff = (size_t)pm * atile; u.boff = (size_t)pn * btile + (size_t)(pm >> 3) * bbatch; u.r0 = pm * BM; u.c0 = pn * BM; u.sel = 0; return true;
;     __device__ __forceinline__ void operator()(Acc& acc, const Unit& u, int wr, int wc, int fr, int fq, PG8_LAS unsigned char* xl) const {
;     ...
;             for (int m = 0; m < 4; ++m) { const int rl = ai * HALF + wr * 64 + m * 16 + fr; const int row = u.r0 + rl; const float s = S[rl], cs = -LOG2E * s, s2 = s * s;
;                 f32x4 o[2];
; #pragma unroll
;                 for (int n = 0; n < 2; ++n) { const f32x4 g = acc[ai][0][m][n], gu = acc[ai][0][m][n] * acc[ai][1][m][n]; f32x4 r;
; #pragma unroll
;                     for (int e = 0; e < 4; ++e) r[e] = gu[e] * (s2 * __builtin_amdgcn_rcpf(1.f + __builtin_amdgcn_exp2f(cs * g[e])));
;                     o[n] = r; }
;                 *(u32x4*)(H + (size_t)row * ldc + (u.c0 >> 1) + wc * 32 + 8 * fq) = pack8(o[0], o[1]); }
	s_cmp_ge_u32 s21, s26
	v_addc_co_u32_e32 v253, vcc, 0, v253, vcc
	v_mul_f32_e32 v8, v12, v8
	v_mul_f32_e32 v9, v13, v9
	v_mul_f32_e32 v10, v14, v10
	v_mfma_f32_16x16x32_bf16 v[112:115], v[196:199], v[204:207], 0
	s_cselect_b32 s21, s29, s28
	s_xor_b32 s21, s21, s27
	s_sub_i32 s26, s21, s27
	v_mul_f32_e32 v11, v15, v11
	v_mul_f32_e32 v0, v4, v0
	v_mul_f32_e32 v1, v5, v1
	v_mul_f32_e32 v2, v6, v2
	v_mfma_f32_16x16x32_bf16 v[104:107], v[188:191], v[212:215], 0
	s_mul_i32 s21, s26, s23
	s_sub_i32 s20, s20, s21
	s_add_i32 s28, s22, s20
	v_mul_f32_e32 v3, v7, v3
	v_mul_f32_e32 v248, 0xbfb8aa3b, v221
	v_mul_f32_e32 v250, v221, v221
	v_mul_f32_e32 v12, v12, v248
	v_mfma_f32_16x16x32_bf16 v[96:99], v[196:199], v[212:215], 0
	s_ashr_i32 s29, s28, 31
	s_ashr_i32 s27, s26, 31
	s_lshl_b64 s[20:21], s[28:29], 19
	v_mul_f32_e32 v13, v13, v248
	v_mul_f32_e32 v14, v14, v248
	v_mul_f32_e32 v15, v15, v248
	v_mul_f32_e32 v4, v4, v248
	v_mfma_f32_16x16x32_bf16 v[88:91], v[188:191], v[222:225], 0
	s_lshl_b64 s[22:23], s[26:27], 19
	s_lshl_b32 s67, s28, 8
	s_lshl_b32 s66, s26, 8
	v_mul_f32_e32 v5, v5, v248
	v_mul_f32_e32 v6, v6, v248
	v_mul_f32_e32 v7, v7, v248
	v_exp_f32_e32 v12, v12
	v_mfma_f32_16x16x32_bf16 v[80:83], v[196:199], v[222:225], 0
	s_add_u32 s26, s37, s20
	s_addc_u32 s27, s42, s21
	s_and_b64 s[28:29], s[6:7], exec
	v_exp_f32_e32 v13, v13
	v_exp_f32_e32 v14, v14
	v_exp_f32_e32 v15, v15
	v_exp_f32_e32 v4, v4
	v_mfma_f32_16x16x32_bf16 v[72:75], v[188:191], v[230:233], 0
	s_cselect_b32 s46, s27, s42
	s_cselect_b32 s47, s26, s37
	s_add_u32 s28, s43, s22
	v_exp_f32_e32 v5, v5
	v_exp_f32_e32 v6, v6
	v_exp_f32_e32 v7, v7
	v_add_f32_e32 v12, 1.0, v12
	v_mfma_f32_16x16x32_bf16 v[64:67], v[196:199], v[230:233], 0
	s_addc_u32 s29, s50, s23
	s_and_b64 s[100:101], s[6:7], exec
	s_cselect_b32 s70, s29, s50
	v_add_f32_e32 v13, 1.0, v13
	v_add_f32_e32 v14, 1.0, v14
	v_add_f32_e32 v15, 1.0, v15
	v_add_f32_e32 v4, 1.0, v4
	v_mfma_f32_16x16x32_bf16 v[120:123], v[192:195], v[208:211], v[120:123]
	s_cselect_b32 s72, s28, s43
	v_add_f32_e32 v5, 1.0, v5
	v_add_f32_e32 v6, 1.0, v6
	v_add_f32_e32 v7, 1.0, v7
	v_rcp_f32_e32 v12, v12
	v_mfma_f32_16x16x32_bf16 v[112:115], v[200:203], v[208:211], v[112:115]
	v_rcp_f32_e32 v13, v13
	v_rcp_f32_e32 v14, v14
	v_rcp_f32_e32 v15, v15
	v_rcp_f32_e32 v4, v4
	v_mfma_f32_16x16x32_bf16 v[104:107], v[192:195], v[216:219], v[104:107]
	v_rcp_f32_e32 v5, v5
	v_rcp_f32_e32 v6, v6
	v_rcp_f32_e32 v7, v7
	v_mul_f32_e32 v12, v250, v12
	v_mfma_f32_16x16x32_bf16 v[96:99], v[200:203], v[216:219], v[96:99]
	v_mul_f32_e32 v13, v250, v13
	v_mul_f32_e32 v14, v250, v14
	v_mul_f32_e32 v15, v250, v15
	v_mul_f32_e32 v4, v250, v4
	v_mfma_f32_16x16x32_bf16 v[88:91], v[192:195], v[226:229], v[88:91]
	v_mul_f32_e32 v5, v250, v5
	v_mul_f32_e32 v6, v250, v6
	v_mul_f32_e32 v7, v250, v7
	v_mul_f32_e32 v8, v8, v12
	v_mfma_f32_16x16x32_bf16 v[80:83], v[200:203], v[226:229], v[80:83]
	v_mul_f32_e32 v9, v9, v13
	v_mul_f32_e32 v10, v10, v14
	v_mul_f32_e32 v11, v11, v15
	v_mul_f32_e32 v0, v0, v4
	v_mfma_f32_16x16x32_bf16 v[72:75], v[192:195], v[234:237], v[72:75]
	v_mul_f32_e32 v1, v1, v5
	v_mul_f32_e32 v2, v2, v6
	v_mul_f32_e32 v3, v3, v7
	v_cvt_pk_bf16_f32 v12, v8, v9
	v_mfma_f32_16x16x32_bf16 v[64:67], v[200:203], v[234:237], v[64:67]
	v_cvt_pk_bf16_f32 v13, v10, v11
	v_cvt_pk_bf16_f32 v14, v0, v1
	v_cvt_pk_bf16_f32 v15, v2, v3
	global_store_dwordx4 v[252:253], v[12:15], off
	s_setprio 0
	s_barrier
	s_add_i32 s68, s54, s51
	v_lshl_add_u64 v[238:239], s[30:31], 0, v[132:133]
	s_mov_b32 m0, s68
	ds_read_b128 v[204:207], v166 offset:16384
	ds_read_b128 v[208:211], v166 offset:17408
	ds_read_b128 v[212:215], v166 offset:18432
	ds_read_b128 v[216:219], v166 offset:19456
	ds_read_b128 v[222:225], v166 offset:20480
	ds_read_b128 v[226:229], v166 offset:21504
	ds_read_b128 v[230:233], v166 offset:22528
	ds_read_b128 v[234:237], v166 offset:23552
	global_load_lds_dwordx4 v[238:239], off
	s_add_i32 m0, s68, 0x2000
	s_add_u32 s76, s30, 0x40000
	v_lshl_add_u64 v[240:241], s[30:31], 0, v[128:129]
	s_addc_u32 s77, s31, 0
	s_add_i32 s68, s62, s51
	global_load_lds_dwordx4 v[240:241], off
	v_lshl_add_u64 v[242:243], s[76:77], 0, v[132:133]
	s_mov_b32 m0, s68
	v_lshl_add_u64 v[244:245], s[34:35], 0, v[130:131]
	global_load_lds_dwordx4 v[242:243], off
	v_lshl_add_u64 v[242:243], s[76:77], 0, v[128:129]
	s_add_i32 m0, s68, 0x2000
	s_nop 0
	global_load_lds_dwordx4 v[242:243], off
	v_lshl_add_u64 v[242:243], s[34:35], 0, v[134:135]
	s_mov_b32 m0, s55
	s_nop 0
	global_load_lds_dwordx4 v[242:243], off
	s_mov_b32 m0, s56
	s_nop 0
	global_load_lds_dwordx4 v[244:245], off
	s_waitcnt vmcnt(10)
	s_waitcnt lgkmcnt(0)
	s_barrier
; #define PG8_STAGE(bufoff, gbase, voff) do { _Pragma("unroll") for (int _i = 0; _i < 2; ++_i) \
;         __builtin_amdgcn_global_load_lds((const unsigned*)((const char*)(gbase) + (voff)[_i]), (PG8_LAS unsigned*)(lds + (bufoff) + ldsw + _i * 8192), 16, 0, 0); } while (0)
; #define PG8_LDA(dst, b, h) do { _Pragma("unroll") for (int m = 0; m < 4; ++m) _Pragma("unroll") for (int k = 0; k < 2; ++k) dst[m][k] = *(const PG8_LAS bf16x8*)(lds + PG8_SA(b, h) + aoff + m * 2048 + k * 1024); } while (0)
; #define PG8_LDB(dst, b, h) do { _Pragma("unroll") for (int n = 0; n < 2; ++n) _Pragma("unroll") for (int k = 0; k < 2; ++k) dst[n][k] = *(const PG8_LAS bf16x8*)(lds + PG8_SB(b, h) + boff + n * 2048 + k * 1024); } while (0)
; #define PG8_MMA(ai, bj, At, Bt) do { __builtin_amdgcn_s_setprio(1); _Pragma("unroll") for (int m = 0; m < 4; ++m) _Pragma("unroll") for (int n = 0; n < 2; ++n) _Pragma("unroll") for (int k = 0; k < 2; ++k) \
;         acc[ai][bj][m][n] = __builtin_amdgcn_mfma_f32_16x16x32_bf16(Bt[n][k], At[m][k], acc[ai][bj][m][n], 0, 0, 0); __builtin_amdgcn_s_setprio(0); } while (0)
; #define PG8_WAIT_V(n) asm volatile("s_waitcnt vmcnt(" #n ")" ::: "memory")
; #define PG8_WAIT_L(n) asm volatile("s_waitcnt lgkmcnt(" #n ")" ::: "memory")
; #define PG8_BAR __builtin_amdgcn_s_barrier()
; #define PG8_SCHED __builtin_amdgcn_sched_barrier(0)
; template <class Epi, class Sched>
; __device__ __forceinline__ void gemm_phase(PG8_LAS unsigned char* lds, PG8_LAS unsigned char* xl, const Gemm g, const Sched& S, const Epi& E) {
;     ...
;             PG8_LDA(At, 0, 1); PG8_STAGE(PG8_SB(0, 0), b2, voffB); PG8_STAGE(PG8_SB(0, 1), b2 + hsB, voffB); PG8_STAGE(PG8_SA(0, 0), a2, voffA);
;             PG8_WAIT_V(8); PG8_WAIT_L(0); PG8_BAR; PG8_MMA(1, 0, At, B0); PG8_MMA(1, 1, At, B1); PG8_BAR; PG8_SCHED;
;             PG8_LDB(B0, 1, 0); PG8_LDB(B1, 1, 1); PG8_SCHED; PG8_LDA(At, 1, 0); PG8_STAGE(PG8_SA(0, 1), a2 + hsA, voffA);
;             PG8_WAIT_V(8); PG8_WAIT_L(0); PG8_BAR; PG8_MMA(0, 0, At, B0); PG8_MMA(0, 1, At, B1); PG8_BAR; PG8_SCHED;
	s_setprio 1
	s_waitcnt lgkmcnt(0)
	v_mfma_f32_16x16x32_bf16 v[60:63], v[170:173], v[204:207], 0
	v_mfma_f32_16x16x32_bf16 v[52:55], v[180:183], v[204:207], 0
	v_mfma_f32_16x16x32_bf16 v[44:47], v[170:173], v[212:215], 0
	v_mfma_f32_16x16x32_bf16 v[36:39], v[180:183], v[212:215], 0
	v_mfma_f32_16x16x32_bf16 v[28:31], v[170:173], v[222:225], 0
	v_mfma_f32_16x16x32_bf16 v[20:23], v[180:183], v[222:225], 0
	v_mfma_f32_16x16x32_bf16 v[12:15], v[170:173], v[230:233], 0
	v_mfma_f32_16x16x32_bf16 v[4:7], v[180:183], v[230:233], 0
	v_mfma_f32_16x16x32_bf16 v[60:63], v[174:177], v[208:211], v[60:63]
	v_mfma_f32_16x16x32_bf16 v[52:55], v[184:187], v[208:211], v[52:55]
	v_mfma_f32_16x16x32_bf16 v[44:47], v[174:177], v[216:219], v[44:47]
	v_mfma_f32_16x16x32_bf16 v[36:39], v[184:187], v[216:219], v[36:39]
	v_mfma_f32_16x16x32_bf16 v[28:31], v[174:177], v[226:229], v[28:31]
	v_mfma_f32_16x16x32_bf16 v[20:23], v[184:187], v[226:229], v[20:23]
	v_mfma_f32_16x16x32_bf16 v[12:15], v[174:177], v[234:237], v[12:15]
	v_mfma_f32_16x16x32_bf16 v[4:7], v[184:187], v[234:237], v[4:7]
	s_setprio 0
	s_setprio 1
	v_mfma_f32_16x16x32_bf16 v[56:59], v[188:191], v[204:207], 0
	v_mfma_f32_16x16x32_bf16 v[48:51], v[196:199], v[204:207], 0
	v_mfma_f32_16x16x32_bf16 v[40:43], v[188:191], v[212:215], 0
	v_mfma_f32_16x16x32_bf16 v[32:35], v[196:199], v[212:215], 0
	v_mfma_f32_16x16x32_bf16 v[24:27], v[188:191], v[222:225], 0
	v_mfma_f32_16x16x32_bf16 v[16:19], v[196:199], v[222:225], 0
	v_mfma_f32_16x16x32_bf16 v[8:11], v[188:191], v[230:233], 0
	v_mfma_f32_16x16x32_bf16 v[0:3], v[196:199], v[230:233], 0
	v_mfma_f32_16x16x32_bf16 v[56:59], v[192:195], v[208:211], v[56:59]
	v_mfma_f32_16x16x32_bf16 v[48:51], v[200:203], v[208:211], v[48:51]
	v_mfma_f32_16x16x32_bf16 v[40:43], v[192:195], v[216:219], v[40:43]
	v_mfma_f32_16x16x32_bf16 v[32:35], v[200:203], v[216:219], v[32:35]
	v_mfma_f32_16x16x32_bf16 v[24:27], v[192:195], v[226:229], v[24:27]
	v_mfma_f32_16x16x32_bf16 v[16:19], v[200:203], v[226:229], v[16:19]
	v_mfma_f32_16x16x32_bf16 v[8:11], v[192:195], v[234:237], v[8:11]
	v_mfma_f32_16x16x32_bf16 v[0:3], v[200:203], v[234:237], v[0:3]
	s_setprio 0
	s_barrier
	s_add_i32 s68, 0, 0x18000
	v_add_u32_e32 v169, s68, v147
	s_add_i32 s76, 0, 0x1c000
	ds_read_b128 v[170:173], v169
	ds_read_b128 v[174:177], v169 offset:1024
	ds_read_b128 v[180:183], v169 offset:2048
	ds_read_b128 v[184:187], v169 offset:3072
	v_add_u32_e32 v169, s76, v147
	ds_read_b128 v[188:191], v169
	ds_read_b128 v[192:195], v169 offset:1024
	ds_read_b128 v[196:199], v169 offset:2048
	ds_read_b128 v[200:203], v169 offset:3072
	s_add_u32 s34, s34, 0x40000
	s_addc_u32 s35, s35, 0
	s_mov_b32 m0, s57
	v_lshl_add_u64 v[246:247], s[34:35], 0, v[134:135]
	ds_read_b128 v[204:207], v166 offset:32768
	ds_read_b128 v[208:211], v166 offset:33792
	ds_read_b128 v[212:215], v166 offset:34816
	ds_read_b128 v[216:219], v166 offset:35840
	ds_read_b128 v[222:225], v166 offset:36864
	ds_read_b128 v[226:229], v166 offset:37888
	ds_read_b128 v[230:233], v166 offset:38912
	ds_read_b128 v[234:237], v166 offset:39936
	global_load_lds_dwordx4 v[246:247], off
	v_lshl_add_u64 v[246:247], s[34:35], 0, v[130:131]
	s_mov_b32 m0, s58
	s_nop 0
	global_load_lds_dwordx4 v[246:247], off
	s_waitcnt vmcnt(10)
	s_waitcnt lgkmcnt(0)
	s_barrier
	s_setprio 1
	s_waitcnt lgkmcnt(0)
	v_mfma_f32_16x16x32_bf16 v[124:127], v[170:173], v[204:207], v[124:127]
	v_mfma_f32_16x16x32_bf16 v[116:119], v[180:183], v[204:207], v[116:119]
	v_mfma_f32_16x16x32_bf16 v[108:111], v[170:173], v[212:215], v[108:111]
	v_mfma_f32_16x16x32_bf16 v[100:103], v[180:183], v[212:215], v[100:103]
	v_mfma_f32_16x16x32_bf16 v[92:95], v[170:173], v[222:225], v[92:95]
	v_mfma_f32_16x16x32_bf16 v[84:87], v[180:183], v[222:225], v[84:87]
	v_mfma_f32_16x16x32_bf16 v[76:79], v[170:173], v[230:233], v[76:79]
	v_mfma_f32_16x16x32_bf16 v[68:71], v[180:183], v[230:233], v[68:71]
	v_mfma_f32_16x16x32_bf16 v[124:127], v[174:177], v[208:211], v[124:127]
	v_mfma_f32_16x16x32_bf16 v[116:119], v[184:187], v[208:211], v[116:119]
	v_mfma_f32_16x16x32_bf16 v[108:111], v[174:177], v[216:219], v[108:111]
	v_mfma_f32_16x16x32_bf16 v[100:103], v[184:187], v[216:219], v[100:103]
	v_mfma_f32_16x16x32_bf16 v[92:95], v[174:177], v[226:229], v[92:95]
	v_mfma_f32_16x16x32_bf16 v[84:87], v[184:187], v[226:229], v[84:87]
	v_mfma_f32_16x16x32_bf16 v[76:79], v[174:177], v[234:237], v[76:79]
	v_mfma_f32_16x16x32_bf16 v[68:71], v[184:187], v[234:237], v[68:71]
	s_setprio 0
	s_setprio 1
	v_mfma_f32_16x16x32_bf16 v[120:123], v[188:191], v[204:207], v[120:123]
	v_mfma_f32_16x16x32_bf16 v[112:115], v[196:199], v[204:207], v[112:115]
	v_mfma_f32_16x16x32_bf16 v[104:107], v[188:191], v[212:215], v[104:107]
	v_mfma_f32_16x16x32_bf16 v[96:99], v[196:199], v[212:215], v[96:99]
	v_mfma_f32_16x16x32_bf16 v[88:91], v[188:191], v[222:225], v[88:91]
	v_mfma_f32_16x16x32_bf16 v[80:83], v[196:199], v[222:225], v[80:83]
	v_mfma_f32_16x16x32_bf16 v[72:75], v[188:191], v[230:233], v[72:75]
	v_mfma_f32_16x16x32_bf16 v[64:67], v[196:199], v[230:233], v[64:67]
	v_mfma_f32_16x16x32_bf16 v[120:123], v[192:195], v[208:211], v[120:123]
	v_mfma_f32_16x16x32_bf16 v[112:115], v[200:203], v[208:211], v[112:115]
	v_mfma_f32_16x16x32_bf16 v[104:107], v[192:195], v[216:219], v[104:107]
	v_mfma_f32_16x16x32_bf16 v[96:99], v[200:203], v[216:219], v[96:99]
	v_mfma_f32_16x16x32_bf16 v[88:91], v[192:195], v[226:229], v[88:91]
	v_mfma_f32_16x16x32_bf16 v[80:83], v[200:203], v[226:229], v[80:83]
	v_mfma_f32_16x16x32_bf16 v[72:75], v[192:195], v[234:237], v[72:75]
	v_mfma_f32_16x16x32_bf16 v[64:67], v[200:203], v[234:237], v[64:67]
	s_setprio 0
	s_barrier
; #define PG8_STAGE(bufoff, gbase, voff) do { _Pragma("unroll") for (int _i = 0; _i < 2; ++_i) \
;         __builtin_amdgcn_global_load_lds((const unsigned*)((const char*)(gbase) + (voff)[_i]), (PG8_LAS unsigned*)(lds + (bufoff) + ldsw + _i * 8192), 16, 0, 0); } while (0)
; #define PG8_LDA(dst, b, h) do { _Pragma("unroll") for (int m = 0; m < 4; ++m) _Pragma("unroll") for (int k = 0; k < 2; ++k) dst[m][k] = *(const PG8_LAS bf16x8*)(lds + PG8_SA(b, h) + aoff + m * 2048 + k * 1024); } while (0)
; #define PG8_MMA(ai, bj, At, Bt) do { __builtin_amdgcn_s_setprio(1); _Pragma("unroll") for (int m = 0; m < 4; ++m) _Pragma("unroll") for (int n = 0; n < 2; ++n) _Pragma("unroll") for (int k = 0; k < 2; ++k) \
;         acc[ai][bj][m][n] = __builtin_amdgcn_mfma_f32_16x16x32_bf16(Bt[n][k], At[m][k], acc[ai][bj][m][n], 0, 0, 0); __builtin_amdgcn_s_setprio(0); } while (0)
; #define PG8_WAIT_V(n) asm volatile("s_waitcnt vmcnt(" #n ")" ::: "memory")
; #define PG8_WAIT_L(n) asm volatile("s_waitcnt lgkmcnt(" #n ")" ::: "memory")
; #define PG8_BAR __builtin_amdgcn_s_barrier()
; #define PG8_SCHED __builtin_amdgcn_sched_barrier(0)
; template <class Epi, class Sched>
; __device__ __forceinline__ void gemm_phase(PG8_LAS unsigned char* lds, PG8_LAS unsigned char* xl, const Gemm g, const Sched& S, const Epi& E) {
;     ...
;             PG8_LDA(At, 1, 1); PG8_STAGE(PG8_SB(1, 0), b3, voffB); PG8_STAGE(PG8_SB(1, 1), b3 + hsB, voffB); PG8_STAGE(PG8_SA(1, 0), a3, voffA);
;             PG8_WAIT_V(8); PG8_WAIT_L(0); PG8_BAR; PG8_MMA(1, 0, At, B0); PG8_MMA(1, 1, At, B1); PG8_BAR; PG8_SCHED;
;         }
	s_add_i32 s34, s68, s51
	v_lshl_add_u64 v[238:239], v[238:239], 0, s[16:17]
	s_mov_b32 m0, s34
	ds_read_b128 v[204:207], v166 offset:49152
	ds_read_b128 v[208:211], v166 offset:50176
	ds_read_b128 v[212:215], v166 offset:51200
	ds_read_b128 v[216:219], v166 offset:52224
	ds_read_b128 v[222:225], v166 offset:53248
	ds_read_b128 v[226:229], v166 offset:54272
	ds_read_b128 v[230:233], v166 offset:55296
	ds_read_b128 v[234:237], v166 offset:56320
	global_load_lds_dwordx4 v[238:239], off
	s_add_i32 m0, s34, 0x2000
	s_add_u32 s30, s30, 0x40080
	v_lshl_add_u64 v[238:239], v[240:241], 0, s[16:17]
	s_addc_u32 s31, s31, 0
	s_add_i32 s34, s76, s51
	global_load_lds_dwordx4 v[238:239], off
	v_lshl_add_u64 v[238:239], s[30:31], 0, v[132:133]
	s_mov_b32 m0, s34
	s_nop 0
	global_load_lds_dwordx4 v[238:239], off
	v_lshl_add_u64 v[238:239], s[30:31], 0, v[128:129]
	s_add_i32 m0, s34, 0x2000
	s_nop 0
	global_load_lds_dwordx4 v[238:239], off
	v_lshl_add_u64 v[238:239], v[242:243], 0, s[16:17]
	s_mov_b32 m0, s59
	s_nop 0
	global_load_lds_dwordx4 v[238:239], off
	v_lshl_add_u64 v[238:239], v[244:245], 0, s[16:17]
	s_mov_b32 m0, s61
	s_nop 0
	global_load_lds_dwordx4 v[238:239], off
	s_waitcnt vmcnt(8)
	s_waitcnt lgkmcnt(0)
	s_barrier
	s_setprio 1
	s_waitcnt lgkmcnt(0)
	v_mfma_f32_16x16x32_bf16 v[60:63], v[170:173], v[204:207], v[60:63]
	v_mfma_f32_16x16x32_bf16 v[52:55], v[180:183], v[204:207], v[52:55]
	v_mfma_f32_16x16x32_bf16 v[44:47], v[170:173], v[212:215], v[44:47]
	v_mfma_f32_16x16x32_bf16 v[36:39], v[180:183], v[212:215], v[36:39]
	v_mfma_f32_16x16x32_bf16 v[28:31], v[170:173], v[222:225], v[28:31]
	v_mfma_f32_16x16x32_bf16 v[20:23], v[180:183], v[222:225], v[20:23]
	v_mfma_f32_16x16x32_bf16 v[12:15], v[170:173], v[230:233], v[12:15]
	v_mfma_f32_16x16x32_bf16 v[4:7], v[180:183], v[230:233], v[4:7]
	v_mfma_f32_16x16x32_bf16 v[60:63], v[174:177], v[208:211], v[60:63]
	v_mfma_f32_16x16x32_bf16 v[52:55], v[184:187], v[208:211], v[52:55]
	v_mfma_f32_16x16x32_bf16 v[44:47], v[174:177], v[216:219], v[44:47]
	v_mfma_f32_16x16x32_bf16 v[36:39], v[184:187], v[216:219], v[36:39]
	v_mfma_f32_16x16x32_bf16 v[28:31], v[174:177], v[226:229], v[28:31]
	v_mfma_f32_16x16x32_bf16 v[20:23], v[184:187], v[226:229], v[20:23]
	v_mfma_f32_16x16x32_bf16 v[12:15], v[174:177], v[234:237], v[12:15]
	v_mfma_f32_16x16x32_bf16 v[4:7], v[184:187], v[234:237], v[4:7]
	s_setprio 0
	s_setprio 1
	v_mfma_f32_16x16x32_bf16 v[56:59], v[188:191], v[204:207], v[56:59]
	v_mfma_f32_16x16x32_bf16 v[48:51], v[196:199], v[204:207], v[48:51]
	v_mfma_f32_16x16x32_bf16 v[40:43], v[188:191], v[212:215], v[40:43]
	v_mfma_f32_16x16x32_bf16 v[32:35], v[196:199], v[212:215], v[32:35]
	v_mfma_f32_16x16x32_bf16 v[24:27], v[188:191], v[222:225], v[24:27]
	v_mfma_f32_16x16x32_bf16 v[16:19], v[196:199], v[222:225], v[16:19]
	v_mfma_f32_16x16x32_bf16 v[8:11], v[188:191], v[230:233], v[8:11]
	v_mfma_f32_16x16x32_bf16 v[0:3], v[196:199], v[230:233], v[0:3]
	v_mfma_f32_16x16x32_bf16 v[56:59], v[192:195], v[208:211], v[56:59]
	v_mfma_f32_16x16x32_bf16 v[48:51], v[200:203], v[208:211], v[48:51]
	v_mfma_f32_16x16x32_bf16 v[40:43], v[192:195], v[216:219], v[40:43]
	v_mfma_f32_16x16x32_bf16 v[32:35], v[200:203], v[216:219], v[32:35]
	v_mfma_f32_16x16x32_bf16 v[24:27], v[192:195], v[226:229], v[24:27]
	v_mfma_f32_16x16x32_bf16 v[16:19], v[200:203], v[226:229], v[16:19]
	v_mfma_f32_16x16x32_bf16 v[8:11], v[192:195], v[234:237], v[8:11]
	v_mfma_f32_16x16x32_bf16 v[0:3], v[200:203], v[234:237], v[0:3]
	s_setprio 0
	s_barrier
	s_add_i32 s75, s75, 2
	s_add_u32 s73, s73, 0x100
	s_addc_u32 s74, s74, 0
	s_add_u32 s2, s2, 0x100
	s_addc_u32 s3, s3, 0
	s_cmp_gt_u32 s75, 13
	s_cbranch_scc1 .Lpeel_after_P8
